# RNN start: the three first-halo loads issued together (one wait instead of three); sparse start: both list-counter loads before the wait; on top of v75
# baseline (speedup 1.0000x reference)
.LBB0_522:
	s_or_b64 exec, exec, s[22:23]
	s_lshl_b32 s4, s2, 2
	s_ashr_i32 s65, s2, 5
	s_and_b32 s66, s4, 0x60
	s_add_i32 s6, s66, s65
	s_cmp_lt_u32 s2, 32
	s_cselect_b64 s[4:5], -1, 0
	s_lshl_b32 s9, s6, 8
	s_lshl_b32 s8, s66, 8
	s_add_i32 s9, s9, -3
	s_lshl_b32 s6, s37, 1
	s_add_u32 s6, s14, s6
	s_addc_u32 s7, s15, 0
	s_add_u32 s34, s6, 0x13000000
	v_lshlrev_b32_e32 v3, 4, v60
	s_addc_u32 s35, s7, 0
	v_and_b32_e32 v4, 0xf0, v3
	v_mov_b32_e32 v5, 0
	s_movk_i32 s6, 0x430
	v_lshl_add_u64 v[4:5], s[34:35], 0, v[4:5]
	s_mov_b64 s[98:99], 0
	s_mov_b64 s[100:101], 0
	v_cmp_gt_i32_e32 vcc, s6, v60
	s_and_saveexec_b64 s[6:7], vcc
	s_cbranch_execz .LBB0_524
	v_ashrrev_i32_e32 v3, 4, v60
	v_cmp_gt_i32_e32 vcc, 3, v3
	v_add_u32_e32 v3, s9, v3
	v_mov_b32_e32 v6, s8
	s_and_b64 vcc, s[4:5], vcc
	v_cndmask_b32_e32 v6, v3, v6, vcc
	v_ashrrev_i32_e32 v7, 31, v6
	v_lshlrev_b64 v[6:7], 11, v[6:7]
	v_lshl_add_u64 v[6:7], v[4:5], 0, v[6:7]
	s_mov_b64 s[98:99], vcc
	global_load_dwordx4 v[48:51], v[6:7], off nt
.LBB0_524:
	s_or_b64 exec, exec, s[6:7]
	s_movk_i32 s6, 0x230
	v_cmp_gt_i32_e32 vcc, s6, v60
	s_and_saveexec_b64 s[6:7], vcc
	s_cbranch_execz .LBB0_526
	v_add_u32_e32 v3, 0x200, v60
	v_ashrrev_i32_e32 v3, 4, v3
	v_cmp_gt_i32_e32 vcc, 3, v3
	v_add_u32_e32 v3, s9, v3
	v_mov_b32_e32 v6, s8
	s_and_b64 vcc, s[4:5], vcc
	v_cndmask_b32_e32 v6, v3, v6, vcc
	v_ashrrev_i32_e32 v7, 31, v6
	v_lshlrev_b64 v[6:7], 11, v[6:7]
	v_lshl_add_u64 v[6:7], v[4:5], 0, v[6:7]
	s_mov_b64 s[100:101], vcc
	global_load_dwordx4 v[52:55], v[6:7], off nt
.LBB0_526:
	s_or_b64 exec, exec, s[6:7]
	v_and_b32_e32 v3, 63, v60
	v_bfe_u32 v6, v60, 4, 2
	v_cmp_gt_i32_e32 vcc, 48, v60
	s_and_saveexec_b64 s[6:7], vcc
	s_cbranch_execz .LBB0_528
	v_add_u32_e32 v7, 0x400, v60
	v_ashrrev_i32_e32 v7, 4, v7
	v_cmp_gt_i32_e32 vcc, 3, v7
	v_add_u32_e32 v7, s9, v7
	v_mov_b32_e32 v8, s8
	s_and_b64 vcc, s[4:5], vcc
	v_cndmask_b32_e32 v8, v7, v8, vcc
	v_ashrrev_i32_e32 v9, 31, v8
	v_lshlrev_b64 v[8:9], 11, v[8:9]
	v_lshl_add_u64 v[4:5], v[4:5], 0, v[8:9]
	global_load_dwordx4 v[56:59], v[4:5], off nt
.LBB0_528:
	s_or_b64 exec, exec, s[6:7]
	s_waitcnt vmcnt(0)
	v_cndmask_b32_e64 v59, v59, 0, vcc
	v_cndmask_b32_e64 v58, v58, 0, vcc
	v_cndmask_b32_e64 v57, v57, 0, vcc
	v_cndmask_b32_e64 v56, v56, 0, vcc
	v_cndmask_b32_e64 v51, v51, 0, s[98:99]
	v_cndmask_b32_e64 v50, v50, 0, s[98:99]
	v_cndmask_b32_e64 v49, v49, 0, s[98:99]
	v_cndmask_b32_e64 v48, v48, 0, s[98:99]
	v_cndmask_b32_e64 v55, v55, 0, s[100:101]
	v_cndmask_b32_e64 v54, v54, 0, s[100:101]
	v_cndmask_b32_e64 v53, v53, 0, s[100:101]
	v_cndmask_b32_e64 v52, v52, 0, s[100:101]
	v_mul_f32_e32 v4, 0xbfb8aa3b, v15
	s_mov_b32 s4, 0xbfb8aa3b
	v_rndne_f32_e32 v5, v4
	v_sub_f32_e32 v7, v4, v5
	v_fma_f32 v4, v15, s4, -v4
	v_fmamk_f32 v4, v15, 0xb2a5705f, v4
	v_add_f32_e32 v4, v7, v4
	v_exp_f32_e32 v4, v4
	v_cvt_i32_f32_e32 v5, v5
	s_mov_b32 s4, 0x42ce8ed0
	v_cmp_nlt_f32_e32 vcc, s4, v15
	s_mov_b32 s4, 0xc2b17218
	v_ldexp_f32 v4, v4, v5
	v_cndmask_b32_e32 v4, 0, v4, vcc
	v_mov_b32_e32 v7, 0x7f800000
	v_cmp_ngt_f32_e32 vcc, s4, v15
	s_mov_b32 s4, 0x3f2aaaab
	v_mul_f32_e32 v64, 0xbfb8aa3b, v63
	v_cndmask_b32_e32 v8, v7, v4, vcc
	v_add_f32_e32 v9, 1.0, v8
	v_add_f32_e32 v4, -1.0, v9
	v_sub_f32_e32 v5, v4, v9
	v_add_f32_e32 v5, 1.0, v5
	v_sub_f32_e32 v4, v8, v4
	v_add_f32_e32 v10, v4, v5
	v_frexp_mant_f32_e32 v11, v9
	v_cvt_f64_f32_e32 v[4:5], v9
	v_frexp_exp_i32_f64_e32 v4, v[4:5]
	v_cmp_gt_f32_e32 vcc, s4, v11
	s_mov_b32 s4, 0x3f317218
	s_add_u32 s38, s14, 0x17000000
	v_subbrev_co_u32_e32 v4, vcc, 0, v4, vcc
	v_sub_u32_e32 v5, 0, v4
	v_ldexp_f32 v9, v9, v5
	v_ldexp_f32 v5, v10, v5
	v_add_f32_e32 v10, -1.0, v9
	v_add_f32_e32 v61, 1.0, v9
	v_add_f32_e32 v11, 1.0, v10
	v_add_f32_e32 v63, -1.0, v61
	v_sub_f32_e32 v11, v9, v11
	v_sub_f32_e32 v9, v9, v63
	v_add_f32_e32 v11, v5, v11
	v_add_f32_e32 v5, v5, v9
	v_add_f32_e32 v9, v61, v5
	v_rcp_f32_e32 v63, v9
	v_add_f32_e32 v15, v10, v11
	v_sub_f32_e32 v10, v10, v15
	v_add_f32_e32 v10, v11, v10
	v_sub_f32_e32 v11, v61, v9
	v_add_f32_e32 v5, v5, v11
	v_mul_f32_e32 v11, v15, v63
	v_mul_f32_e32 v61, v9, v11
	v_fma_f32 v65, v11, v9, -v61
	v_fmac_f32_e32 v65, v11, v5
	v_add_f32_e32 v66, v61, v65
	v_sub_f32_e32 v68, v15, v66
	v_sub_f32_e32 v15, v15, v68
	v_sub_f32_e32 v61, v66, v61
	v_sub_f32_e32 v15, v15, v66
	v_add_f32_e32 v10, v10, v15
	v_sub_f32_e32 v15, v61, v65
	v_add_f32_e32 v10, v15, v10
	v_add_f32_e32 v15, v68, v10
	v_mul_f32_e32 v61, v63, v15
	v_mul_f32_e32 v65, v9, v61
	v_fma_f32 v9, v61, v9, -v65
	v_fmac_f32_e32 v9, v61, v5
	v_sub_f32_e32 v5, v68, v15
	v_add_f32_e32 v5, v10, v5
	v_add_f32_e32 v10, v65, v9
	v_sub_f32_e32 v66, v15, v10
	v_sub_f32_e32 v15, v15, v66
	v_sub_f32_e32 v65, v10, v65
	v_sub_f32_e32 v10, v15, v10
	v_add_f32_e32 v5, v5, v10
	v_sub_f32_e32 v9, v65, v9
	v_cvt_f32_i32_e32 v4, v4
	v_add_f32_e32 v5, v9, v5
	v_add_f32_e32 v9, v11, v61
	v_add_f32_e32 v5, v66, v5
	v_sub_f32_e32 v10, v9, v11
	v_mul_f32_e32 v5, v63, v5
	v_sub_f32_e32 v10, v61, v10
	v_add_f32_e32 v5, v10, v5
	v_mul_f32_e32 v61, 0x3f317218, v4
	v_add_f32_e32 v10, v9, v5
	v_fma_f32 v63, v4, s4, -v61
	v_fmamk_f32 v4, v4, 0xb102e308, v63
	v_sub_f32_e32 v9, v10, v9
	v_mul_f32_e32 v11, v10, v10
	v_mov_b32_e32 v15, 0x3ecc95a3
	v_sub_f32_e32 v5, v5, v9
	v_add_f32_e32 v9, v61, v4
	v_fmac_f32_e32 v15, 0x3e9b6dac, v11
	v_sub_f32_e32 v61, v9, v61
	v_fmaak_f32 v15, v11, v15, 0x3f2aaada
	v_sub_f32_e32 v4, v4, v61
	v_ldexp_f32 v61, v10, 1
	v_mul_f32_e32 v10, v10, v11
	v_mul_f32_e32 v10, v10, v15
	v_add_f32_e32 v11, v61, v10
	v_sub_f32_e32 v15, v11, v61
	v_ldexp_f32 v5, v5, 1
	v_sub_f32_e32 v10, v10, v15
	v_add_f32_e32 v5, v5, v10
	v_add_f32_e32 v10, v11, v5
	v_sub_f32_e32 v11, v10, v11
	v_sub_f32_e32 v5, v5, v11
	v_add_f32_e32 v11, v9, v10
	v_sub_f32_e32 v15, v11, v9
	v_sub_f32_e32 v61, v11, v15
	v_sub_f32_e32 v9, v9, v61
	v_sub_f32_e32 v10, v10, v15
	v_add_f32_e32 v9, v10, v9
	v_add_f32_e32 v10, v4, v5
	s_addc_u32 s39, s15, 0
	v_sub_f32_e32 v15, v10, v4
	s_add_u32 s52, s20, 0x4000000
	v_sub_f32_e32 v61, v10, v15
	s_addc_u32 s53, s21, 0
	s_lshl_b32 s12, s27, 2
	v_sub_f32_e32 v4, v4, v61
	v_sub_f32_e32 v5, v5, v15
	s_add_u32 s12, s14, s12
	v_add_f32_e32 v4, v5, v4
	v_add_f32_e32 v5, v10, v9
	s_addc_u32 s13, s15, 0
	v_add_f32_e32 v9, v11, v5
	s_add_u32 s54, s12, 0x14000
	v_sub_f32_e32 v10, v9, v11
	s_addc_u32 s55, s13, 0
	s_load_dwordx2 s[12:13], s[0:1], 0xb0
	v_sub_f32_e32 v5, v5, v10
	s_cmp_lt_u32 s33, 64
	s_mov_b32 s5, 0x7f800000
	v_add_f32_e32 v4, v4, v5
	v_lshl_add_u64 v[0:1], v[0:1], 3, s[14:15]
	s_cselect_b64 s[56:57], -1, 0
	s_ashr_i32 s14, s78, 6
	v_add_f32_e32 v4, v9, v4
	v_cmp_neq_f32_e32 vcc, s5, v8
	s_mov_b32 s4, 0x33800000
	s_lshl_b32 s68, s78, 2
	s_ashr_i32 s15, s14, 31
	v_cndmask_b32_e32 v4, v7, v4, vcc
	v_cmp_lt_f32_e64 vcc, |v8|, s4
	s_and_b32 s69, s68, 28
	s_lshl_b32 s70, s88, 5
	s_lshl_b64 s[14:15], s[14:15], 24
	v_cndmask_b32_e32 v4, v4, v8, vcc
	s_waitcnt lgkmcnt(0)
	s_add_u32 s14, s12, s14
	v_mul_f32_e32 v4, 0xc1000000, v4
	s_mov_b64 s[8:9], 0x2900000
	s_addc_u32 s15, s13, s15
	s_lshl_b32 s16, s26, 1
	v_mul_f32_e32 v68, 0x3fb8aa3b, v4
	v_lshlrev_b32_e32 v4, 1, v14
	v_lshl_add_u64 v[76:77], v[0:1], 0, s[8:9]
	v_mul_u32_u24_e32 v1, 0x440, v6
	s_add_u32 s14, s14, s16
	v_add3_u32 v61, 0, v4, v1
	s_addc_u32 s15, s15, 0
	v_and_b32_e32 v4, 64, v12
	v_cmp_gt_u32_e64 s[6:7], 32, v3
	v_cmp_gt_u32_e64 s[8:9], 16, v3
	v_or_b32_e32 v1, 48, v3
	s_add_u32 s58, s14, 0x7000000
	v_xor_b32_e32 v3, 32, v12
	v_add_u32_e32 v4, 64, v4
	s_addc_u32 s59, s15, 0
	v_cmp_lt_i32_e32 vcc, v3, v4
	v_mul_f32_e32 v62, 0xbfb8aa3b, v62
	v_add_u32_e32 v2, 0, v2
	v_and_b32_e32 v5, 16, v60
	v_mul_u32_u24_e32 v0, 0x110, v13
	v_mul_u32_u24_e32 v1, 0x110, v1
	v_cndmask_b32_e32 v3, v12, v3, vcc
	s_add_u32 s62, s12, 0x10000
	v_mov_b32_e32 v67, 0
	s_mov_b32 s24, 0
	s_mov_b32 s36, 0x3fb8aa3b
	v_mov_b32_e32 v63, v62
	v_mov_b32_e32 v70, v62
	v_mov_b32_e32 v71, v62
	v_mov_b32_e32 v65, v64
	v_mov_b32_e32 v72, v64
	v_mov_b32_e32 v73, v64
	v_mov_b32_e32 v69, v68
	v_mov_b32_e32 v74, v68
	v_mov_b32_e32 v75, v68
	v_cmp_eq_u32_e64 s[4:5], 0, v5
	v_cmp_eq_u32_e64 s[10:11], 0, v60
	s_movk_i32 s67, 0x110
	v_lshlrev_b32_e32 v92, 2, v3
	s_mov_b64 s[60:61], 0x10000
	s_addc_u32 s63, s13, 0
	s_movk_i32 s71, 0x430
	s_movk_i32 s72, 0x230
	v_mov_b32_e32 v93, 1
	s_mov_b32 s73, 0xff61b1e6
	s_movk_i32 s74, 0x80
	v_add_u32_e32 v94, v2, v0
	v_add_u32_e32 v95, v2, v1
	v_mov_b32_e32 v96, 0xff61b1e6
	v_mov_b32_e32 v113, 0
	s_mov_b32 s75, 0
	s_branch .LBB0_530

.LBB0_788:
	global_load_dword v1, v[2:3], off sc1
	global_load_dword v4, v[2:3], off offset:2048 sc1
	s_waitcnt vmcnt(0)
	ds_write_b32 v5, v1
	ds_write_b32 v5, v4 offset:2048
